# v63 + attention main loop: the MFMA-free middle of each KV step rescheduled so the first accumulator chain's subtracts fill the wait for the last QK^T MFMA (s_nop 6 / s_nop 3 gone, 7 + 4 idle slots fe
# speedup vs baseline: 1.0117x; 1.0117x over previous
.LBB0_1604:
	v_add_u32_e32 v0, s22, v244
	ds_read_b64_tr_b16 v[208:209], v0 offset:24576
	ds_read_b64_tr_b16 v[210:211], v0 offset:25088
	s_waitcnt lgkmcnt(9)
	v_mfma_f32_32x32x16_bf16 v[112:127], v[204:207], v[172:175], 0
	v_add_f32_e32 v2, v87, v88
	v_cvt_pk_bf16_f32 v156, v96, v97
	v_cvt_pk_bf16_f32 v157, v98, v99
	ds_read_b64_tr_b16 v[204:205], v0 offset:28672
	ds_read_b64_tr_b16 v[206:207], v0 offset:29184
	v_add_f32_e32 v2, v89, v2
	v_cvt_pk_bf16_f32 v158, v100, v101
	v_cvt_pk_bf16_f32 v159, v102, v103
	s_waitcnt lgkmcnt(10)
	v_mfma_f32_32x32x16_bf16 v[128:143], v[200:203], v[172:175], 0
	ds_read_b64_tr_b16 v[10:11], v0 offset:25600
	ds_read_b64_tr_b16 v[12:13], v0 offset:26112
	s_waitcnt lgkmcnt(11)
	v_mfma_f32_32x32x16_bf16 v[112:127], v[196:199], v[168:171], v[112:127]
	v_add_f32_e32 v2, v90, v2
	v_cvt_pk_bf16_f32 v152, v104, v105
	v_cvt_pk_bf16_f32 v153, v106, v107
	ds_read_b64_tr_b16 v[6:7], v0 offset:29696
	ds_read_b64_tr_b16 v[8:9], v0 offset:30208
	v_add_f32_e32 v14, v91, v2
	v_cvt_pk_bf16_f32 v154, v108, v109
	v_cvt_pk_bf16_f32 v155, v110, v111
	s_waitcnt lgkmcnt(12)
	v_mfma_f32_32x32x16_bf16 v[128:143], v[192:195], v[168:171], v[128:143]
	ds_read_b64_tr_b16 v[2:3], v0 offset:26624
	ds_read_b64_tr_b16 v[4:5], v0 offset:27136
	s_waitcnt lgkmcnt(13)
	v_mfma_f32_32x32x16_bf16 v[112:127], v[188:191], v[164:167], v[112:127]
	v_add_f32_e32 v14, v92, v14
	v_cvt_pk_bf16_f32 v148, v80, v81
	v_cvt_pk_bf16_f32 v149, v82, v83
	ds_read_b64_tr_b16 v[196:197], v0 offset:30720
	ds_read_b64_tr_b16 v[198:199], v0 offset:31232
	v_add_f32_e32 v14, v93, v14
	v_cvt_pk_bf16_f32 v150, v84, v85
	v_cvt_pk_bf16_f32 v151, v86, v87
	s_waitcnt lgkmcnt(14)
	v_mfma_f32_32x32x16_bf16 v[128:143], v[184:187], v[164:167], v[128:143]
	ds_read_b64_tr_b16 v[192:193], v0 offset:27648
	ds_read_b64_tr_b16 v[194:195], v0 offset:28160
	s_waitcnt lgkmcnt(14)
	v_mfma_f32_32x32x16_bf16 v[112:127], v[180:183], v[160:163], v[112:127]
	v_add_f32_e32 v14, v94, v14
	v_cvt_pk_bf16_f32 v144, v88, v89
	v_cvt_pk_bf16_f32 v145, v90, v91
	ds_read_b64_tr_b16 v[188:189], v0 offset:31744
	ds_read_b64_tr_b16 v[190:191], v0 offset:32256
	v_add_f32_e32 v96, v95, v14
	v_cvt_pk_bf16_f32 v146, v92, v93
	v_cvt_pk_bf16_f32 v147, v94, v95
	v_mfma_f32_32x32x16_bf16 v[128:143], v[176:179], v[160:163], v[128:143]
	s_nop 2
	v_add_f32_e64 v80, v112, -v228
	v_add_f32_e64 v81, v113, -v228
	v_pk_add_f32 v[98:99], v[114:115], v[228:229] op_sel_hi:[1,0] neg_lo:[0,1] neg_hi:[0,1]
	v_pk_add_f32 v[100:101], v[116:117], v[228:229] op_sel_hi:[1,0] neg_lo:[0,1] neg_hi:[0,1]
	v_pk_add_f32 v[102:103], v[118:119], v[228:229] op_sel_hi:[1,0] neg_lo:[0,1] neg_hi:[0,1]
	v_pk_add_f32 v[104:105], v[120:121], v[228:229] op_sel_hi:[1,0] neg_lo:[0,1] neg_hi:[0,1]
	v_pk_add_f32 v[106:107], v[122:123], v[228:229] op_sel_hi:[1,0] neg_lo:[0,1] neg_hi:[0,1]
	v_pk_add_f32 v[108:109], v[124:125], v[228:229] op_sel_hi:[1,0] neg_lo:[0,1] neg_hi:[0,1]
	v_pk_add_f32 v[110:111], v[126:127], v[228:229] op_sel_hi:[1,0] neg_lo:[0,1] neg_hi:[0,1]
	v_max_f32_e32 v97, v80, v81
	s_add_u32 s30, s16, s10
	v_pk_add_f32 v[14:15], v[128:129], v[228:229] op_sel_hi:[1,0] neg_lo:[0,1] neg_hi:[0,1]
	v_max3_f32 v112, v98, v99, v100
	s_addc_u32 s31, s17, s11
	v_pk_add_f32 v[82:83], v[130:131], v[228:229] op_sel_hi:[1,0] neg_lo:[0,1] neg_hi:[0,1]
	v_max3_f32 v97, v97, v101, v102
	s_add_u32 s22, s30, 0x80000
	v_pk_add_f32 v[84:85], v[132:133], v[228:229] op_sel_hi:[1,0] neg_lo:[0,1] neg_hi:[0,1]
	v_max3_f32 v112, v112, v103, v104
	s_addc_u32 s23, s31, 0
	v_pk_add_f32 v[86:87], v[134:135], v[228:229] op_sel_hi:[1,0] neg_lo:[0,1] neg_hi:[0,1]
	v_max3_f32 v97, v97, v105, v106
	s_add_i32 s24, s29, s57
	v_pk_add_f32 v[88:89], v[136:137], v[228:229] op_sel_hi:[1,0] neg_lo:[0,1] neg_hi:[0,1]
	v_max3_f32 v112, v112, v107, v108
	s_add_u32 s62, s18, s10
	v_pk_add_f32 v[90:91], v[138:139], v[228:229] op_sel_hi:[1,0] neg_lo:[0,1] neg_hi:[0,1]
	v_max3_f32 v97, v97, v109, v110
	s_addc_u32 s63, s19, s11
	v_pk_add_f32 v[92:93], v[140:141], v[228:229] op_sel_hi:[1,0] neg_lo:[0,1] neg_hi:[0,1]
	v_max3_f32 v112, v112, v111, v14
	v_pk_add_f32 v[94:95], v[142:143], v[228:229] op_sel_hi:[1,0] neg_lo:[0,1] neg_hi:[0,1]
	v_max3_f32 v97, v97, v15, v82
	v_max3_f32 v112, v112, v83, v84
	v_max3_f32 v97, v97, v85, v86
	v_max3_f32 v112, v112, v87, v88
	v_max3_f32 v97, v97, v89, v90
	v_max3_f32 v112, v112, v91, v92
	v_max3_f32 v97, v97, v94, v95
	s_mov_b32 s25, m0
	s_mov_b32 m0, s24
	s_nop 0
	global_load_lds_dwordx4 v241, s[22:23]
	s_mov_b32 m0, s25
	s_add_u32 s22, s62, 0x40000
	v_add_f32_e32 v116, v224, v96
	v_max3_f32 v96, v97, v93, v112
	s_addc_u32 s23, s63, 0
	s_add_i32 s24, s28, s58
	v_mov_b32_e32 v97, v96
	s_add_u32 s64, s20, s10
	s_nop 0
	v_permlane32_swap_b32_e32 v96, v97
	s_addc_u32 s65, s21, s11
	s_mov_b32 s25, m0
	s_mov_b32 m0, s24
	s_nop 0
	global_load_lds_dwordx4 v242, s[22:23]
	s_mov_b32 m0, s25
	s_add_u32 s22, s64, 0x40000
	v_max_f32_e32 v96, v96, v97
	s_addc_u32 s23, s65, 0
	s_add_i32 s24, s28, s59
	s_mov_b32 s25, m0
	s_mov_b32 m0, s24
	s_nop 0
	global_load_lds_dwordx4 v242, s[22:23]
	s_mov_b32 m0, s25
	v_cmp_lt_f32_e32 vcc, s35, v96
	s_cmp_lg_u64 vcc, 0
	s_cselect_b64 s[22:23], -1, 0
	s_cbranch_vccnz .LBB0_1612

.LBB0_1607:
	s_add_i32 s22, s28, 0x2000
	s_cmpk_lg_i32 s28, 0x4000
	s_cselect_b32 s61, s22, 0
	v_add_f32_e32 v15, v116, v14
	v_add_u32_e32 v14, s29, v244
	ds_read_b64_tr_b16 v[196:197], v14 offset:24576
	ds_read_b64_tr_b16 v[198:199], v14 offset:25088
	v_add_f32_e32 v132, v87, v88
	v_cvt_pk_bf16_f32 v156, v96, v97
	v_cvt_pk_bf16_f32 v157, v98, v99
	v_mfma_f32_32x32x16_bf16 v[112:127], v[112:115], v[172:175], 0
	ds_read_b64_tr_b16 v[192:193], v14 offset:28672
	ds_read_b64_tr_b16 v[194:195], v14 offset:29184
	v_add_f32_e32 v96, v89, v132
	v_cvt_pk_bf16_f32 v158, v100, v101
	v_cvt_pk_bf16_f32 v159, v102, v103
	v_mfma_f32_32x32x16_bf16 v[128:143], v[128:131], v[172:175], 0
	ds_read_b64_tr_b16 v[188:189], v14 offset:25600
	ds_read_b64_tr_b16 v[190:191], v14 offset:26112
	v_add_f32_e32 v96, v90, v96
	v_cvt_pk_bf16_f32 v152, v104, v105
	v_cvt_pk_bf16_f32 v153, v106, v107
	v_mfma_f32_32x32x16_bf16 v[112:127], v[184:187], v[168:171], v[112:127]
	ds_read_b64_tr_b16 v[184:185], v14 offset:29696
	ds_read_b64_tr_b16 v[186:187], v14 offset:30208
	v_add_f32_e32 v96, v91, v96
	v_cvt_pk_bf16_f32 v154, v108, v109
	v_cvt_pk_bf16_f32 v155, v110, v111
	v_mfma_f32_32x32x16_bf16 v[128:143], v[176:179], v[168:171], v[128:143]
	ds_read_b64_tr_b16 v[176:177], v14 offset:26624
	ds_read_b64_tr_b16 v[178:179], v14 offset:27136
	v_add_f32_e32 v96, v92, v96
	v_cvt_pk_bf16_f32 v148, v80, v81
	v_cvt_pk_bf16_f32 v149, v82, v83
	v_mfma_f32_32x32x16_bf16 v[112:127], v[180:183], v[164:167], v[112:127]
	ds_read_b64_tr_b16 v[212:213], v14 offset:30720
	ds_read_b64_tr_b16 v[214:215], v14 offset:31232
	v_add_f32_e32 v80, v93, v96
	v_cvt_pk_bf16_f32 v150, v84, v85
	v_cvt_pk_bf16_f32 v151, v86, v87
	v_mfma_f32_32x32x16_bf16 v[128:143], v[6:9], v[164:167], v[128:143]
	ds_read_b64_tr_b16 v[208:209], v14 offset:27648
	ds_read_b64_tr_b16 v[210:211], v14 offset:28160
	v_add_f32_e32 v80, v94, v80
	v_cvt_pk_bf16_f32 v144, v88, v89
	v_cvt_pk_bf16_f32 v145, v90, v91
	v_mfma_f32_32x32x16_bf16 v[112:127], v[10:13], v[160:163], v[112:127]
	ds_read_b64_tr_b16 v[6:7], v14 offset:31744
	ds_read_b64_tr_b16 v[8:9], v14 offset:32256
	v_add_f32_e32 v10, v95, v80
	v_cvt_pk_bf16_f32 v146, v92, v93
	v_cvt_pk_bf16_f32 v147, v94, v95
	v_mfma_f32_32x32x16_bf16 v[128:143], v[2:5], v[160:163], v[128:143]
	s_nop 5
	v_add_f32_e64 v4, v112, -v228
	v_add_f32_e64 v5, v113, -v228
	v_pk_add_f32 v[98:99], v[114:115], v[228:229] op_sel_hi:[1,0] neg_lo:[0,1] neg_hi:[0,1]
	v_pk_add_f32 v[100:101], v[116:117], v[228:229] op_sel_hi:[1,0] neg_lo:[0,1] neg_hi:[0,1]
	v_pk_add_f32 v[102:103], v[118:119], v[228:229] op_sel_hi:[1,0] neg_lo:[0,1] neg_hi:[0,1]
	v_pk_add_f32 v[104:105], v[120:121], v[228:229] op_sel_hi:[1,0] neg_lo:[0,1] neg_hi:[0,1]
	v_pk_add_f32 v[106:107], v[122:123], v[228:229] op_sel_hi:[1,0] neg_lo:[0,1] neg_hi:[0,1]
	v_pk_add_f32 v[108:109], v[124:125], v[228:229] op_sel_hi:[1,0] neg_lo:[0,1] neg_hi:[0,1]
	v_pk_add_f32 v[110:111], v[126:127], v[228:229] op_sel_hi:[1,0] neg_lo:[0,1] neg_hi:[0,1]
	v_max_f32_e32 v11, v4, v5
	s_add_u32 s22, s30, 0xa0000
	v_pk_add_f32 v[2:3], v[128:129], v[228:229] op_sel_hi:[1,0] neg_lo:[0,1] neg_hi:[0,1]
	v_max3_f32 v12, v98, v99, v100
	v_pk_add_f32 v[82:83], v[130:131], v[228:229] op_sel_hi:[1,0] neg_lo:[0,1] neg_hi:[0,1]
	v_max3_f32 v11, v11, v101, v102
	v_pk_add_f32 v[84:85], v[132:133], v[228:229] op_sel_hi:[1,0] neg_lo:[0,1] neg_hi:[0,1]
	v_max3_f32 v12, v12, v103, v104
	v_pk_add_f32 v[86:87], v[134:135], v[228:229] op_sel_hi:[1,0] neg_lo:[0,1] neg_hi:[0,1]
	v_max3_f32 v11, v11, v105, v106
	v_pk_add_f32 v[88:89], v[136:137], v[228:229] op_sel_hi:[1,0] neg_lo:[0,1] neg_hi:[0,1]
	v_max3_f32 v12, v12, v107, v108
	v_pk_add_f32 v[90:91], v[138:139], v[228:229] op_sel_hi:[1,0] neg_lo:[0,1] neg_hi:[0,1]
	v_max3_f32 v11, v11, v109, v110
	v_pk_add_f32 v[92:93], v[140:141], v[228:229] op_sel_hi:[1,0] neg_lo:[0,1] neg_hi:[0,1]
	v_max3_f32 v12, v12, v111, v2
	v_pk_add_f32 v[94:95], v[142:143], v[228:229] op_sel_hi:[1,0] neg_lo:[0,1] neg_hi:[0,1]
	v_max3_f32 v11, v11, v3, v82
	v_max3_f32 v12, v12, v83, v84
	v_max3_f32 v11, v11, v85, v86
	v_max3_f32 v12, v12, v87, v88
	v_max3_f32 v11, v11, v89, v90
	v_max3_f32 v12, v12, v91, v92
	v_max3_f32 v11, v11, v94, v95
	v_max3_f32 v11, v11, v93, v12
	s_addc_u32 s23, s31, 0
	s_add_i32 s24, s28, s57
	v_mov_b32_e32 v12, v11
	s_mov_b32 s25, m0
	s_mov_b32 m0, s24
	s_nop 0
	global_load_lds_dwordx4 v241, s[22:23]
	s_mov_b32 m0, s25
	s_add_u32 s22, s62, 0x60000
	s_nop 0
	v_permlane32_swap_b32_e32 v11, v12
	s_addc_u32 s23, s63, 0
	s_add_i32 s24, s61, s58
	s_mov_b32 s25, m0
	s_mov_b32 m0, s24
	s_nop 0
	global_load_lds_dwordx4 v242, s[22:23]
	s_mov_b32 m0, s25
	s_add_u32 s22, s64, 0x60000
	v_max_f32_e32 v11, v11, v12
	s_addc_u32 s23, s65, 0
	s_add_i32 s24, s61, s59
	s_mov_b32 s25, m0
	s_mov_b32 m0, s24
	s_nop 0
	global_load_lds_dwordx4 v242, s[22:23]
	s_mov_b32 m0, s25
	v_cmp_lt_f32_e32 vcc, s35, v11
	s_cmp_lg_u64 vcc, 0
	v_add_f32_e32 v10, v15, v10
	s_cselect_b64 s[22:23], -1, 0
	s_cbranch_vccnz .LBB0_1615
